# ret_out: query fragment loads issued before the staging barrier instead of after it
# speedup vs baseline: 1.0051x; 1.0051x over previous
; #define LAUNDER_V(x) asm volatile("" : "+v"(x))
; __device__ __forceinline__ void ret_out(const Params& P, int l, unsigned char* lds, int u, int tid) {
;     ...
;     const int b = u >> 6, h = (u >> 4) & 3, np = u & 15;
;     const float lgf2 = -expf(lr[h]) * LOG2E, lgb2 = -expf(lr[4 + h]) * LOG2E;
;     const size_t t0 = (size_t)b * S + np * 256;
; #pragma unroll
;     for (int it = 0; it < 4; ++it) {
;         const int idx = tid + 512 * it;
;         { const int part = idx & 7, key = (idx >> 3) & 127, ck = idx >> 10;
;           const u32x4 kv = *(const u32x4*)(ZR + (t0 + ck * 128 + key) * 1024 + 256 + h * 64 + part * 8);
;           *(u32x4*)(Kl + (ck * 128 + key) * RK + part * 8) = kv; }
;         { const int key = idx & 127, e8 = ((idx >> 7) & 7) * 8, ck = idx >> 10;
;           const u32x4 v = *(const u32x4*)(ZR + (t0 + ck * 128 + key) * 1024 + 512 + h * 64 + e8);
; #pragma unroll
;           for (int i = 0; i < 8; ++i) Vt[(ck * 64 + e8 + i) * RS + key] = (bf16_t)((v[i >> 1] >> (16 * (i & 1))) & 0xffffu); }
;     }
; __global__ void __launch_bounds__(512, 2) fwd_megakernel(Params Pdummy) {
;     ...
;                     for (;;) {
;                         __syncthreads();
;                         if (tid == 0) *slot = atomicAdd(ctrl + qx * 64, 1u);
;                         __syncthreads();
;                         const unsigned u = *slot;
;                         if (u >= qn) break;
;                         int tq = tid; LAUNDER_V(tq);
;                         if (xs < 8) { const int bh = qx * 4 + (int)(u >> 4); attn_unit(P, lds, bh >> 3, bh & 7, (int)(u & 15), tq); }
;                         else ret_out(P, l, lds, (int)u, tq);
.LBB0_140:
	s_or_b64 exec, exec, s[6:7]
	s_mov_b64 s[6:7], src_shared_base
	s_add_i32 s6, 0, 0x20400
	s_cmp_lg_u32 s6, -1
	s_cselect_b32 s6, s6, 0
	s_cselect_b32 s7, s7, 0
	v_mov_b32_e32 v0, s6
	v_mov_b32_e32 v1, s7
	s_waitcnt lgkmcnt(0)
	s_barrier
	flat_load_dword v0, v[0:1] sc0 sc1
	s_waitcnt vmcnt(0)
	s_mov_b64 s[6:7], -1
	s_waitcnt lgkmcnt(0)
	v_cmp_lt_u32_e32 vcc, v0, v220
	s_and_saveexec_b64 s[26:27], vcc
	s_cbranch_execz .LBB0_137
	v_mov_b32_e32 v49, v217
	s_nop 0
	v_bfe_u32 v223, v49, 5, 1
	v_add_u32_e32 v28, 0x200, v49
	v_and_b32_e32 v222, 31, v49
	v_lshlrev_b32_e32 v64, 3, v223
	v_lshlrev_b32_e32 v162, 4, v223
	s_and_saveexec_b64 s[6:7], s[34:35]
	s_xor_b64 s[8:9], exec, s[6:7]
	s_cbranch_execz .LBB0_147
	s_mov_b64 s[6:7], s[0:1]
	s_load_dwordx2 s[6:7], s[6:7], 0xf0
	v_and_b32_e32 v79, 15, v0
	v_ashrrev_i32_e32 v46, 10, v49
	v_lshrrev_b32_e32 v67, 6, v0
	v_bfe_u32 v78, v0, 4, 2
	v_lshlrev_b32_e32 v0, 8, v79
	v_lshlrev_b32_e32 v34, 7, v46
	s_mov_b64 s[10:11], s[0:1]
	v_lshl_or_b32 v152, v67, 12, v0
	v_lshlrev_b32_e32 v0, 4, v49
	v_ashrrev_i32_e32 v35, 31, v34
	v_and_b32_e32 v32, 0x70, v0
	v_and_b32_e32 v44, 0x7f, v49
	v_bfe_u32 v45, v49, 3, 7
	v_lshl_add_u64 v[0:1], v[34:35], 0, v[152:153]
	s_load_dwordx2 s[92:93], s[10:11], 0xf0
	s_waitcnt lgkmcnt(0)
	s_add_u32 s10, s6, 0xcc00000
	v_or_b32_e32 v2, v0, v45
	v_mov_b32_e32 v3, v1
	v_or_b32_e32 v0, v0, v44
	v_ashrrev_i32_e32 v50, 10, v28
	s_mov_b64 s[12:13], s[0:1]
	s_addc_u32 s11, s7, 0
	v_lshlrev_b64 v[2:3], 11, v[2:3]
	v_lshrrev_b32_e32 v4, 4, v49
	v_lshlrev_b64 v[0:1], 11, v[0:1]
	v_lshlrev_b32_e32 v38, 7, v50
	v_lshl_add_u64 v[2:3], s[10:11], 0, v[2:3]
	v_lshlrev_b32_e32 v36, 7, v78
	v_mov_b32_e32 v37, v153
	v_and_b32_e32 v47, 56, v4
	v_lshl_add_u64 v[0:1], s[10:11], 0, v[0:1]
	v_ashrrev_i32_e32 v39, 31, v38
	s_load_dwordx2 s[6:7], s[12:13], 0xf0
	s_mov_b64 s[12:13], s[0:1]
	v_lshl_add_u64 v[2:3], v[2:3], 0, v[36:37]
	v_mov_b32_e32 v33, v153
	v_lshl_add_u64 v[0:1], v[0:1], 0, v[36:37]
	v_lshlrev_b32_e32 v16, 1, v47
	v_mov_b32_e32 v17, v153
	v_bfe_u32 v48, v28, 3, 7
	v_lshl_add_u64 v[8:9], v[38:39], 0, v[152:153]
	v_add_u32_e32 v18, 0x400, v49
	s_mov_b64 s[28:29], s[0:1]
	v_lshl_add_u64 v[2:3], v[2:3], 0, v[32:33]
	v_lshl_add_u64 v[4:5], v[0:1], 0, v[16:17]
	v_or_b32_e32 v10, v8, v48
	v_mov_b32_e32 v11, v9
	v_or_b32_e32 v8, v8, v44
	v_ashrrev_i32_e32 v51, 10, v18
	s_load_dwordx2 s[12:13], s[12:13], 0xd0
	global_load_dwordx4 v[0:3], v[2:3], off offset:512
	s_nop 0
	global_load_dwordx4 v[4:7], v[4:5], off offset:1024
	v_lshlrev_b64 v[10:11], 11, v[10:11]
	v_lshrrev_b32_e32 v12, 4, v28
	v_lshlrev_b64 v[8:9], 11, v[8:9]
	v_lshlrev_b32_e32 v40, 7, v51
	v_lshl_add_u64 v[10:11], s[10:11], 0, v[10:11]
	v_and_b32_e32 v39, 56, v12
	v_lshl_add_u64 v[8:9], s[10:11], 0, v[8:9]
	v_ashrrev_i32_e32 v41, 31, v40
	v_add_u32_e32 v30, 0x600, v49
	v_lshl_add_u64 v[10:11], v[10:11], 0, v[36:37]
	v_lshl_add_u64 v[8:9], v[8:9], 0, v[36:37]
	v_lshlrev_b32_e32 v12, 1, v39
	v_mov_b32_e32 v13, v153
	v_lshl_add_u64 v[18:19], v[40:41], 0, v[152:153]
	v_ashrrev_i32_e32 v52, 10, v30
	v_lshl_add_u64 v[10:11], v[10:11], 0, v[32:33]
	v_lshl_add_u64 v[12:13], v[8:9], 0, v[12:13]
	v_or_b32_e32 v20, v18, v45
	v_mov_b32_e32 v21, v19
	v_or_b32_e32 v18, v18, v44
	v_lshlrev_b32_e32 v42, 7, v52
	global_load_dwordx4 v[8:11], v[10:11], off offset:512
	s_nop 0
	global_load_dwordx4 v[12:15], v[12:13], off offset:1024
	v_lshlrev_b64 v[20:21], 11, v[20:21]
	v_lshlrev_b64 v[18:19], 11, v[18:19]
	v_ashrrev_i32_e32 v43, 31, v42
	v_lshl_add_u64 v[20:21], s[10:11], 0, v[20:21]
	v_lshl_add_u64 v[18:19], s[10:11], 0, v[18:19]
	v_bfe_u32 v41, v30, 3, 7
	v_lshl_add_u64 v[28:29], v[42:43], 0, v[152:153]
	v_lshl_add_u64 v[20:21], v[20:21], 0, v[36:37]
	v_lshl_add_u64 v[18:19], v[18:19], 0, v[36:37]
	v_or_b32_e32 v24, v28, v41
	v_mov_b32_e32 v25, v29
	v_lshl_add_u64 v[20:21], v[20:21], 0, v[32:33]
	v_lshl_add_u64 v[22:23], v[18:19], 0, v[16:17]
	v_lshlrev_b64 v[24:25], 11, v[24:25]
	global_load_dwordx4 v[16:19], v[20:21], off offset:512
	s_nop 0
	global_load_dwordx4 v[20:23], v[22:23], off offset:1024
	v_lshl_add_u64 v[24:25], s[10:11], 0, v[24:25]
	v_or_b32_e32 v28, v28, v44
	v_lshl_add_u64 v[24:25], v[24:25], 0, v[36:37]
	v_lshrrev_b32_e32 v30, 4, v30
	v_lshlrev_b64 v[28:29], 11, v[28:29]
	v_lshl_add_u64 v[24:25], v[24:25], 0, v[32:33]
	v_and_b32_e32 v33, 56, v30
	v_lshl_add_u64 v[28:29], s[10:11], 0, v[28:29]
	global_load_dwordx4 v[24:27], v[24:25], off offset:512
	v_lshl_add_u64 v[28:29], v[28:29], 0, v[36:37]
	v_lshlrev_b32_e32 v30, 1, v33
	v_mov_b32_e32 v31, v153
	v_lshl_add_u64 v[28:29], v[28:29], 0, v[30:31]
	global_load_dwordx4 v[28:31], v[28:29], off offset:1024
	s_lshl_b32 s18, s91, 2
	s_waitcnt lgkmcnt(0)
	s_add_u32 s18, s12, s18
	s_addc_u32 s19, s13, 0
	v_lshlrev_b32_e32 v35, 2, v78
	v_add_u32_e32 v32, 0, v32
	v_or_b32_e32 v34, v34, v45
	s_movk_i32 s20, 0x90
	s_load_dwordx2 s[12:13], s[28:29], 0xd8
	global_load_dword v43, v35, s[18:19]
	global_load_dword v65, v35, s[18:19] offset:16
	v_mad_u64_u32 v[34:35], s[18:19], v34, s20, v[32:33]
	v_lshl_add_u32 v44, v44, 1, 0
	s_movk_i32 s21, 0x110
	v_ashrrev_i32_e32 v81, 8, v49
	v_mov_b32_e32 v163, v153
	s_waitcnt vmcnt(9)
; __device__ __forceinline__ void ret_out(const Params& P, int l, unsigned char* lds, int u, int tid) {
;     ...
;     const float lgf2 = -expf(lr[h]) * LOG2E, lgb2 = -expf(lr[4 + h]) * LOG2E;
;     const size_t t0 = (size_t)b * S + np * 256;
; #pragma unroll
;     for (int it = 0; it < 4; ++it) {
;         const int idx = tid + 512 * it;
;         { const int part = idx & 7, key = (idx >> 3) & 127, ck = idx >> 10;
;           const u32x4 kv = *(const u32x4*)(ZR + (t0 + ck * 128 + key) * 1024 + 256 + h * 64 + part * 8);
;           *(u32x4*)(Kl + (ck * 128 + key) * RK + part * 8) = kv; }
;         { const int key = idx & 127, e8 = ((idx >> 7) & 7) * 8, ck = idx >> 10;
;           const u32x4 v = *(const u32x4*)(ZR + (t0 + ck * 128 + key) * 1024 + 512 + h * 64 + e8);
; #pragma unroll
;           for (int i = 0; i < 8; ++i) Vt[(ck * 64 + e8 + i) * RS + key] = (bf16_t)((v[i >> 1] >> (16 * (i & 1))) & 0xffffu); }
;     }
;     __syncthreads();
;     const int ck = wid >> 2, c0 = 32 * (wid & 3);
;     const size_t tc = t0 + ck * 128;
;     const int n = np * 2 + ck;
;     bf16x8 qr[4];
; #pragma unroll
;     for (int s = 0; s < 4; ++s) qr[s] = *(const bf16x8*)(ZR + (tc + c0 + r32) * 1024 + h * 64 + 16 * s + 8 * hi);
;     const bf16_t* Kc = Kl + ck * 128 * RK; const bf16_t* Vc = Vt + ck * 64 * RS;
;     f32x16 o0, o1;
; #pragma unroll
;     for (int i = 0; i < 16; ++i) { o0[i] = 0.f; o1[i] = 0.f; }
	ds_write_b128 v34, v[0:3]
	v_lshl_or_b32 v0, v46, 6, v47
	v_mad_u64_u32 v[0:1], s[18:19], v0, s21, v[44:45]
	s_waitcnt vmcnt(8)
	ds_write_b16 v0, v4 offset:36864
	ds_write_b16_d16_hi v0, v4 offset:37136
	ds_write_b16 v0, v5 offset:37408
	ds_write_b16_d16_hi v0, v5 offset:37680
	ds_write_b16 v0, v6 offset:37952
	ds_write_b16_d16_hi v0, v6 offset:38224
	ds_write_b16 v0, v7 offset:38496
	ds_write_b16_d16_hi v0, v7 offset:38768
	v_or_b32_e32 v0, v38, v48
	v_mad_u64_u32 v[0:1], s[18:19], v0, s20, v[32:33]
	s_waitcnt vmcnt(7)
	ds_write_b128 v0, v[8:11]
	v_lshl_or_b32 v0, v50, 6, v39
	v_mad_u64_u32 v[0:1], s[18:19], v0, s21, v[44:45]
	s_waitcnt vmcnt(6)
	ds_write_b16 v0, v12 offset:36864
	ds_write_b16_d16_hi v0, v12 offset:37136
	ds_write_b16 v0, v13 offset:37408
	ds_write_b16_d16_hi v0, v13 offset:37680
	ds_write_b16 v0, v14 offset:37952
	ds_write_b16_d16_hi v0, v14 offset:38224
	ds_write_b16 v0, v15 offset:38496
	ds_write_b16_d16_hi v0, v15 offset:38768
	v_or_b32_e32 v0, v40, v45
	v_mad_u64_u32 v[0:1], s[18:19], v0, s20, v[32:33]
	s_waitcnt vmcnt(5)
	ds_write_b128 v0, v[16:19]
	v_lshl_or_b32 v0, v51, 6, v47
	v_mad_u64_u32 v[0:1], s[18:19], v0, s21, v[44:45]
	s_waitcnt vmcnt(4)
	ds_write_b16 v0, v20 offset:36864
	ds_write_b16_d16_hi v0, v20 offset:37136
	ds_write_b16 v0, v21 offset:37408
	ds_write_b16_d16_hi v0, v21 offset:37680
	ds_write_b16 v0, v22 offset:37952
	ds_write_b16_d16_hi v0, v22 offset:38224
	ds_write_b16 v0, v23 offset:38496
	ds_write_b16_d16_hi v0, v23 offset:38768
	v_or_b32_e32 v0, v42, v41
	v_mad_u64_u32 v[0:1], s[18:19], v0, s20, v[32:33]
	s_waitcnt vmcnt(3)
	ds_write_b128 v0, v[24:27]
	v_lshl_or_b32 v0, v52, 6, v33
	v_mad_u64_u32 v[0:1], s[18:19], v0, s21, v[44:45]
	s_waitcnt vmcnt(2)
	ds_write_b16 v0, v28 offset:36864
	ds_write_b16_d16_hi v0, v28 offset:37136
	ds_write_b16 v0, v29 offset:37408
	ds_write_b16_d16_hi v0, v29 offset:37680
	ds_write_b16 v0, v30 offset:37952
	ds_write_b16_d16_hi v0, v30 offset:38224
	ds_write_b16 v0, v31 offset:38496
	ds_write_b16_d16_hi v0, v31 offset:38768
	v_lshrrev_b32_e32 v0, 1, v49
	v_and_b32_e32 v66, 0x60, v0
	v_lshlrev_b32_e32 v0, 7, v81
	v_ashrrev_i32_e32 v1, 31, v0
	v_lshl_add_u64 v[68:69], v[0:1], 0, v[152:153]
	v_or_b32_e32 v80, v66, v222
	v_or_b32_e32 v0, v68, v80
	v_mov_b32_e32 v1, v69
	v_lshlrev_b64 v[0:1], 11, v[0:1]
	v_lshl_add_u64 v[0:1], s[10:11], 0, v[0:1]
	v_lshl_add_u64 v[0:1], v[0:1], 0, v[36:37]
	v_lshl_add_u64 v[0:1], v[0:1], 0, v[162:163]
	global_load_dwordx4 v[60:63], v[0:1], off
	global_load_dwordx4 v[56:59], v[0:1], off offset:32
	global_load_dwordx4 v[52:55], v[0:1], off offset:64
	global_load_dwordx4 v[48:51], v[0:1], off offset:96
	s_waitcnt lgkmcnt(0)
	s_barrier
	s_waitcnt vmcnt(5)
	v_mul_f32_e32 v0, 0x3fb8aa3b, v43
	v_fma_f32 v1, v43, s53, -v0
	v_rndne_f32_e32 v2, v0
	v_fmac_f32_e32 v1, 0x32a5705f, v43
	v_sub_f32_e32 v0, v0, v2
	v_add_f32_e32 v0, v0, v1
	v_cvt_i32_f32_e32 v1, v2
	s_waitcnt vmcnt(4)
	v_mul_f32_e32 v2, 0x3fb8aa3b, v65
	v_fma_f32 v3, v65, s53, -v2
	v_rndne_f32_e32 v4, v2
	v_exp_f32_e32 v0, v0
	v_fmac_f32_e32 v3, 0x32a5705f, v65
	v_sub_f32_e32 v2, v2, v4
	v_add_f32_e32 v2, v2, v3
	v_exp_f32_e32 v2, v2
	v_cvt_i32_f32_e32 v3, v4
	v_ldexp_f32 v1, v0, v1
	v_cmp_ngt_f32_e32 vcc, s58, v43
	v_mul_u32_u24_e32 v4, 0x90, v222
	v_ldexp_f32 v2, v2, v3
	v_cndmask_b32_e32 v1, 0, v1, vcc
	v_cmp_nlt_f32_e32 vcc, s40, v43
	s_movk_i32 s18, 0x4800
	v_mov_b32_e32 v0, 0
	v_cndmask_b32_e32 v1, v210, v1, vcc
	v_cmp_ngt_f32_e32 vcc, s58, v65
	v_mul_f32_e32 v82, 0xbfb8aa3b, v1
	v_mul_i32_i24_e32 v1, 0x4800, v81
	v_cndmask_b32_e32 v2, 0, v2, vcc
	v_cmp_nlt_f32_e32 vcc, s40, v65
	v_mad_u32_u24 v1, v222, s21, v1
	v_or_b32_e32 v1, v1, v64
	v_cndmask_b32_e32 v2, v210, v2, vcc
	v_mul_f32_e32 v83, 0xbfb8aa3b, v2
	v_lshlrev_b32_e32 v2, 10, v81
	v_mul_i32_i24_e32 v3, -4, v223
	v_mad_i32_i24 v4, v81, s18, v4
	v_sub_u32_e32 v1, v1, v2
	s_add_i32 s18, 0, 0x9000
	v_lshlrev_b32_e32 v65, 6, v78
	v_add3_u32 v84, v4, v162, 0
	v_add_u32_e32 v85, s18, v1
	v_add3_u32 v86, v3, v66, v222
	s_mov_b32 s18, 0
	v_mov_b32_e32 v1, v0
	v_mov_b32_e32 v2, v0
	v_mov_b32_e32 v3, v0
	v_mov_b32_e32 v4, v0
	v_mov_b32_e32 v5, v0
	v_mov_b32_e32 v6, v0
	v_mov_b32_e32 v7, v0
	v_mov_b32_e32 v8, v0
	v_mov_b32_e32 v9, v0
	v_mov_b32_e32 v10, v0
	v_mov_b32_e32 v11, v0
	v_mov_b32_e32 v12, v0
	v_mov_b32_e32 v13, v0
	v_mov_b32_e32 v14, v0
	v_mov_b32_e32 v15, v0
	v_mov_b32_e32 v16, v0
	v_mov_b32_e32 v17, v0
	v_mov_b32_e32 v18, v0
	v_mov_b32_e32 v19, v0
	v_mov_b32_e32 v20, v0
	v_mov_b32_e32 v21, v0
	v_mov_b32_e32 v22, v0
	v_mov_b32_e32 v23, v0
	v_mov_b32_e32 v24, v0
	v_mov_b32_e32 v25, v0
	v_mov_b32_e32 v26, v0
	v_mov_b32_e32 v27, v0
	v_mov_b32_e32 v28, v0
	v_mov_b32_e32 v29, v0
	v_mov_b32_e32 v30, v0
	v_mov_b32_e32 v31, v0
